# baseline (speedup 1.0000x reference)
.LBB0_1200:
	s_mov_b64 s[6:7], 0
	s_andn2_b64 vcc, exec, s[6:7]
	s_cbranch_vccnz .LBB0_1205
	s_addk_i32 s10, 0xb00
	v_cvt_f32_u32_e32 v0, s10
	v_mul_f32_e32 v1, v0, v15
	v_trunc_f32_e32 v1, v1
	v_fma_f32 v0, -v1, v14, v0
	v_cvt_u32_f32_e32 v1, v1
	v_cmp_ge_f32_e64 s[6:7], |v0|, v14
	s_cmp_lg_u64 s[6:7], 0
	v_readfirstlane_b32 s8, v1
	s_addc_u32 s6, s8, 0
	s_mul_i32 s6, s6, s0
	s_sub_i32 s6, s10, s6
	s_and_b32 s6, s6, 0x1fff
	s_sub_i32 s1, s1, s6
	s_ashr_i32 s6, s1, 31
	s_and_b32 s6, s6, s0
	s_add_i32 s1, s6, s1
	s_cmpk_gt_i32 s1, 0xaff
	s_cbranch_scc1 .LBB0_1205
	s_mov_b64 s[12:13], s[70:71]
	v_readlane_b32 s68, v241, 0
	s_lshl_b64 s[4:5], s[24:25], 1
	v_readlane_b32 s6, v241, 53
	v_readlane_b32 s72, v241, 4
	v_readlane_b32 s73, v241, 5
	s_add_u32 s40, s6, s4
	v_readlane_b32 s4, v241, 54
	v_readlane_b32 s74, v241, 6
	v_readlane_b32 s75, v241, 7
	s_mov_b64 s[44:45], s[72:73]
	s_addc_u32 s6, s4, s5
	s_mov_b64 s[46:47], s[74:75]
	v_readlane_b32 s4, v236, 22
	s_add_u32 s4, s46, s4
	v_lshlrev_b32_e32 v0, 4, v12
	s_addc_u32 s5, s47, s83
	v_and_b32_e32 v128, 0xf0, v0
	v_and_b32_e32 v2, 7, v13
	v_lshrrev_b32_e32 v3, 3, v12
	v_lshl_add_u64 v[60:61], s[4:5], 0, v[128:129]
	v_readlane_b32 s4, v241, 61
	v_mul_u32_u24_e32 v4, 0x820, v2
	v_lshlrev_b32_e32 v5, 2, v3
	v_add_u32_e32 v0, s4, v128
	v_add3_u32 v63, s4, v4, v5
	s_mul_i32 s4, s1, 0xb0000
	v_readlane_b32 s69, v241, 1
	s_add_i32 s4, s4, 0x9a000
	s_movk_i32 s69, 0x2c00
	v_lshrrev_b32_e32 v62, 4, v12
	v_mov_b32_e32 v4, s4
	v_mul_u32_u24_e32 v1, 0x104, v62
	v_mad_u32_u24 v3, v3, s69, v4
	v_readlane_b32 s8, v237, 51
	s_and_b32 s41, s6, 0xffff
	v_lshl_or_b32 v64, v2, 4, v3
	s_lshl_b32 s4, s1, 6
	s_lshl_b32 s5, s0, 6
	v_add_u32_e32 v65, v0, v1
	v_readlane_b32 s10, v237, 53
	v_readlane_b32 s11, v237, 54
	v_readlane_b32 s70, v241, 2
	v_readlane_b32 s71, v241, 3
	v_readlane_b32 s9, v237, 52

.LBB0_1493:
	v_readlane_b32 s0, v240, 26
	v_readlane_b32 s1, v240, 27
	v_readlane_b32 s4, v236, 18
	s_cmp_lg_u32 s4, 3
	s_cselect_b64 s[4:5], -1, 0
	s_and_b64 s[0:1], s[0:1], s[4:5]
	s_andn2_b64 vcc, exec, s[0:1]
	v_readlane_b32 s0, v236, 18
	v_readlane_b32 s1, v236, 19
	s_mov_b32 s4, s0
	s_mul_hi_u32 s0, s0, 0x1600000
	s_mul_i32 s1, s4, 0x1600000
	s_cbranch_vccnz .LBB0_1498
	v_readlane_b32 s4, v240, 30
	v_readlane_b32 s5, v240, 31
	v_mov_b32_e32 v0, v190
	s_andn2_b64 vcc, exec, s[4:5]
	s_cbranch_vccnz .LBB0_1498
	v_readlane_b32 s68, v241, 0
	v_readlane_b32 s4, v241, 53
	v_readlane_b32 s72, v241, 4
	v_readlane_b32 s73, v241, 5
	s_add_u32 s40, s4, s1
	v_readlane_b32 s4, v241, 54
	v_readlane_b32 s74, v241, 6
	v_readlane_b32 s75, v241, 7
	s_mov_b64 s[44:45], s[72:73]
	s_addc_u32 s6, s4, s0
	s_mov_b64 s[46:47], s[74:75]
	v_readlane_b32 s4, v236, 22
	s_add_u32 s4, s46, s4
	v_lshlrev_b32_e32 v1, 4, v0
	s_addc_u32 s5, s47, s83
	v_bfe_u32 v62, v0, 4, 2
	v_and_b32_e32 v128, 0xf0, v1
	v_and_b32_e32 v3, 7, v0
	v_bfe_u32 v0, v0, 3, 3
	v_lshl_add_u64 v[60:61], s[4:5], 0, v[128:129]
	v_readlane_b32 s4, v241, 61
	v_mul_u32_u24_e32 v4, 0x820, v3
	v_lshlrev_b32_e32 v5, 2, v0
	v_readlane_b32 s69, v241, 1
	v_add_u32_e32 v1, s4, v128
	v_add3_u32 v63, s4, v4, v5
	v_readlane_b32 s4, v237, 56
	s_movk_i32 s69, 0x2c00
	v_mul_u32_u24_e32 v2, 0x104, v62
	v_mov_b32_e32 v4, s4
	v_mad_u32_u24 v0, v0, s69, v4
	v_readlane_b32 s5, v237, 55
	v_readlane_b32 s8, v237, 51
	s_and_b32 s41, s6, 0xffff
	v_lshl_or_b32 v64, v3, 4, v0
	s_lshl_b32 s4, s5, 6
	v_add_u32_e32 v65, v1, v2
	v_readlane_b32 s10, v237, 53
	v_readlane_b32 s11, v237, 54
	v_readlane_b32 s70, v241, 2
	v_readlane_b32 s71, v241, 3
	v_readlane_b32 s9, v237, 52
